# speedup vs baseline: 1.0205x; 1.0205x over previous
; #define LAS __attribute__((address_space(3)))
; __device__ __forceinline__ float half_max(float m) { auto rr = __builtin_amdgcn_permlane32_swap(__float_as_uint(m), __float_as_uint(m), false, false); return fmaxf(__uint_as_float(rr[0]), __uint_as_float(rr[1])); }
; __device__ __forceinline__ void softmax_pv(f32x16& s0, f32x16& s1, float& mref, f32x16& negm, float& lsum, f32x16 (&o)[2], LAS float* fac, const bf16x8 (&vf)[2][4], bool first, int r32, int hi) {
;     float ma = fmaxf(fmaxf(s0[0], s0[1]), s0[2]), mb = fmaxf(fmaxf(s1[0], s1[1]), s1[2]);
; #pragma unroll
;     for (int r = 3; r < 15; r += 2) { ma = fmaxf(fmaxf(ma, s0[r]), s0[r + 1]); mb = fmaxf(fmaxf(mb, s1[r]), s1[r + 1]); }
;     float mx = fmaxf(fmaxf(ma, mb), fmaxf(s0[15], s1[15]));
;     mx = half_max(mx);
;     if (__builtin_expect(first || __any(mx > 16.0f), 0)) {
; template <bool DIFF>
; __device__ __forceinline__ void attn_item(const Params& p, int l, int I, LAS unsigned char* lds, const int tid) {
;     ...
;       for (int sub = 0; sub < 2; ++sub) {
;         const int t = 2 * st + sub;
;         const LAS unsigned char* sb = lds + (st & 1) * AT_SLOT + sub * AT_SUB;
;         const LAS unsigned char* kb = sb + hi * 1024 + r32 * 16;
;         const LAS unsigned char* vb = sb + AT_V + vlane;
;         bf16x8 vf[2][4];
; #pragma unroll
;         for (int dh = 0; dh < 2; ++dh)
; #pragma unroll
;             for (int k = 0; k < 4; ++k) { const s16x4 lo = vtr(vb + dh * 4096 + k * 1024), hh = vtr(vb + dh * 4096 + k * 1024 + 512);
;                 vf[dh][k] = (bf16x8){lo[0], lo[1], lo[2], lo[3], hh[0], hh[1], hh[2], hh[3]}; }
;         bf16x8 kf[NQ][2];
; #pragma unroll
;         for (int d0 = 0; d0 < NQ; ++d0) { kf[d0][0] = *(const LAS bf16x8*)(kb + d0 * 2048); kf[d0][1] = *(const LAS bf16x8*)(kb + d0 * 2048 + 512); }
;         {
;             if (DIFF) {
; #pragma unroll
;                 for (int r = 0; r < 16; ++r) negm1[r] = -mref1;
;             }
;             f32x16 s0 = negm1, s1 = negm1;
; #pragma unroll
;             for (int d0 = 0; d0 < NQ; ++d0) {
;                 s0 = __builtin_amdgcn_mfma_f32_32x32x16_bf16(kf[d0][0], qf[d0], s0, 0, 0, 0);
;                 s1 = __builtin_amdgcn_mfma_f32_32x32x16_bf16(kf[d0][1], qf[d0], s1, 0, 0, 0);
;             }
;             softmax_pv(s0, s1, mref1, negm1, l1, o1, scr, vf, t == 0, r32, hi);
.LBB0_495:
	s_bitcmp1_b32 s34, 0
	s_cselect_b32 s18, 0xa000, 0
	v_add_u32_e32 v64, s18, v181
	v_add_u32_e32 v187, v64, v182
	v_add_u32_e32 v128, s18, v175
	v_add3_u32 v128, v128, v176, v177
	v_add_u32_e32 v163, v128, v178
	ds_read_b128 v[234:237], v187
	ds_read_b128 v[238:241], v187 offset:512
	ds_read_b128 v[242:245], v187 offset:2048
	ds_read_b128 v[188:191], v187 offset:2560
	s_waitcnt lgkmcnt(0)
	v_mfma_f32_32x32x16_bf16 v[80:95], v[234:237], v[104:107], v[194:209]
	v_mfma_f32_32x32x16_bf16 v[80:95], v[242:245], v[112:115], v[80:95]
	v_mfma_f32_32x32x16_bf16 v[64:79], v[238:241], v[104:107], v[194:209]
	v_mfma_f32_32x32x16_bf16 v[64:79], v[188:191], v[112:115], v[64:79]
	ds_read_b64_tr_b16 v[128:129], v163 offset:12288
	ds_read_b64_tr_b16 v[130:131], v163 offset:12800
	ds_read_b64_tr_b16 v[144:145], v163 offset:16384
	ds_read_b64_tr_b16 v[146:147], v163 offset:16896
	ds_read_b64_tr_b16 v[132:133], v163 offset:13312
	ds_read_b64_tr_b16 v[134:135], v163 offset:13824
	ds_read_b64_tr_b16 v[148:149], v163 offset:17408
	ds_read_b64_tr_b16 v[150:151], v163 offset:17920
	ds_read_b128 v[234:237], v187 offset:4096
	ds_read_b128 v[238:241], v187 offset:4608
	ds_read_b128 v[242:245], v187 offset:6144
	ds_read_b128 v[188:191], v187 offset:6656
	s_waitcnt lgkmcnt(7)
	ds_read_b64_tr_b16 v[136:137], v163 offset:14336
	ds_read_b64_tr_b16 v[138:139], v163 offset:14848
	ds_read_b64_tr_b16 v[152:153], v163 offset:18432
	ds_read_b64_tr_b16 v[154:155], v163 offset:18944
	ds_read_b64_tr_b16 v[140:141], v163 offset:15360
	ds_read_b64_tr_b16 v[142:143], v163 offset:15872
	ds_read_b64_tr_b16 v[156:157], v163 offset:19456
	ds_read_b64_tr_b16 v[158:159], v163 offset:19968
	s_cmp_eq_u32 s34, 0
	s_cbranch_scc1 .Ldr_first_00
.Ldr_cont_00:
	v_exp_f32_e32 v80, v80
	v_exp_f32_e32 v81, v81
	v_exp_f32_e32 v82, v82
	v_exp_f32_e32 v83, v83
	v_exp_f32_e32 v84, v84
	v_exp_f32_e32 v85, v85
	v_exp_f32_e32 v86, v86
	v_exp_f32_e32 v87, v87
	v_cvt_pk_bf16_f32 v210, v80, v81
	v_cvt_pk_bf16_f32 v211, v82, v83
	v_cvt_pk_bf16_f32 v212, v84, v85
	v_cvt_pk_bf16_f32 v213, v86, v87
	v_add_f32_e32 v214, v80, v82
	v_add_f32_e32 v215, v81, v83
	v_add_f32_e32 v214, v214, v84
	v_add_f32_e32 v215, v215, v85
	v_add_f32_e32 v214, v214, v86
	v_add_f32_e32 v215, v215, v87
	v_mfma_f32_32x32x16_bf16 v[32:47], v[210:213], v[128:131], v[32:47]
	v_mfma_f32_32x32x16_bf16 v[48:63], v[210:213], v[144:147], v[48:63]
	v_exp_f32_e32 v88, v88
	v_exp_f32_e32 v89, v89
	v_exp_f32_e32 v90, v90
	v_exp_f32_e32 v91, v91
	v_exp_f32_e32 v92, v92
	v_exp_f32_e32 v93, v93
	v_exp_f32_e32 v94, v94
	v_exp_f32_e32 v95, v95
	v_cvt_pk_bf16_f32 v248, v88, v89
	v_cvt_pk_bf16_f32 v249, v90, v91
	v_cvt_pk_bf16_f32 v250, v92, v93
	v_cvt_pk_bf16_f32 v251, v94, v95
	v_add_f32_e32 v214, v214, v88
	v_add_f32_e32 v215, v215, v89
	v_add_f32_e32 v214, v214, v90
	v_add_f32_e32 v215, v215, v91
	v_add_f32_e32 v214, v214, v92
	v_add_f32_e32 v215, v215, v93
	v_add_f32_e32 v214, v214, v94
	v_add_f32_e32 v215, v215, v95
	s_waitcnt lgkmcnt(12)
	v_mfma_f32_32x32x16_bf16 v[32:47], v[248:251], v[132:135], v[32:47]
	v_mfma_f32_32x32x16_bf16 v[48:63], v[248:251], v[148:151], v[48:63]
	s_waitcnt lgkmcnt(8)
	v_mfma_f32_32x32x16_bf16 v[80:95], v[234:237], v[120:123], v[218:233]
	v_mfma_f32_32x32x16_bf16 v[80:95], v[242:245], v[124:127], v[80:95]
	v_exp_f32_e32 v64, v64
	v_exp_f32_e32 v65, v65
	v_exp_f32_e32 v66, v66
	v_exp_f32_e32 v67, v67
	v_exp_f32_e32 v68, v68
	v_exp_f32_e32 v69, v69
	v_exp_f32_e32 v70, v70
	v_exp_f32_e32 v71, v71
	v_cvt_pk_bf16_f32 v210, v64, v65
	v_cvt_pk_bf16_f32 v211, v66, v67
	v_cvt_pk_bf16_f32 v212, v68, v69
	v_cvt_pk_bf16_f32 v213, v70, v71
	v_add_f32_e32 v214, v214, v64
	v_add_f32_e32 v215, v215, v65
	v_add_f32_e32 v214, v214, v66
	v_add_f32_e32 v215, v215, v67
	v_add_f32_e32 v214, v214, v68
	v_add_f32_e32 v215, v215, v69
	v_add_f32_e32 v214, v214, v70
	v_add_f32_e32 v215, v215, v71
	s_waitcnt lgkmcnt(4)
	v_mfma_f32_32x32x16_bf16 v[32:47], v[210:213], v[136:139], v[32:47]
	v_mfma_f32_32x32x16_bf16 v[48:63], v[210:213], v[152:155], v[48:63]
	v_exp_f32_e32 v72, v72
	v_exp_f32_e32 v73, v73
	v_exp_f32_e32 v74, v74
	v_exp_f32_e32 v75, v75
	v_exp_f32_e32 v76, v76
	v_exp_f32_e32 v77, v77
	v_exp_f32_e32 v78, v78
	v_exp_f32_e32 v79, v79
	v_cvt_pk_bf16_f32 v248, v72, v73
	v_cvt_pk_bf16_f32 v249, v74, v75
	v_cvt_pk_bf16_f32 v250, v76, v77
	v_cvt_pk_bf16_f32 v251, v78, v79
	v_add_f32_e32 v214, v214, v72
	v_add_f32_e32 v215, v215, v73
	v_add_f32_e32 v214, v214, v74
	v_add_f32_e32 v215, v215, v75
	v_add_f32_e32 v214, v214, v76
	v_add_f32_e32 v215, v215, v77
	v_add_f32_e32 v214, v214, v78
	v_add_f32_e32 v215, v215, v79
	v_mfma_f32_32x32x16_bf16 v[64:79], v[238:241], v[120:123], v[218:233]
	v_mfma_f32_32x32x16_bf16 v[64:79], v[188:191], v[124:127], v[64:79]
	s_waitcnt lgkmcnt(0)
	v_mfma_f32_32x32x16_bf16 v[32:47], v[248:251], v[140:143], v[32:47]
	v_mfma_f32_32x32x16_bf16 v[48:63], v[248:251], v[156:159], v[48:63]
	v_add_f32_e32 v214, v214, v215
	v_add_f32_e32 v162, v162, v214
	v_cmp_lt_f32_e32 vcc, 0x47800000, v214
	s_cbranch_vccnz .Ldp_00
.Ldpc_00:
	ds_read_b128 v[234:237], v187 offset:20480
	ds_read_b128 v[238:241], v187 offset:20992
	ds_read_b128 v[242:245], v187 offset:22528
	ds_read_b128 v[188:191], v187 offset:23040
	s_nop 1
	s_cmp_eq_u32 s34, 0
	s_cbranch_scc1 .Ldr_first_01
; #define LAS __attribute__((address_space(3)))
; __device__ __forceinline__ unsigned cvt_pk_bf16(float lo, float hi) { const f32x2 v = {lo, hi}; const bf16x2_t b = __builtin_convertvector(v, bf16x2_t); return __builtin_bit_cast(unsigned, b); }
; __device__ __forceinline__ void softmax_pv(f32x16& s0, f32x16& s1, float& mref, f32x16& negm, float& lsum, f32x16 (&o)[2], LAS float* fac, const bf16x8 (&vf)[2][4], bool first, int r32, int hi) {
;     ...
;     float ps0 = 0.f, ps1 = 0.f;
; #pragma unroll
;     for (int r = 0; r < 16; ++r) { s0[r] = __builtin_amdgcn_exp2f(s0[r]); s1[r] = __builtin_amdgcn_exp2f(s1[r]); ps0 += s0[r]; ps1 += s1[r]; }
;     lsum += ps0 + ps1;
;     bf16x8 pa[4];
; #pragma unroll
;     for (int k = 0; k < 4; ++k) {
;         const f32x16& s = (k < 2) ? s0 : s1; const int rb = 8 * (k & 1);
;         u32x4 w; w.x = cvt_pk_bf16(s[rb + 0], s[rb + 1]); w.y = cvt_pk_bf16(s[rb + 2], s[rb + 3]); w.z = cvt_pk_bf16(s[rb + 4], s[rb + 5]); w.w = cvt_pk_bf16(s[rb + 6], s[rb + 7]);
;         pa[k] = __builtin_bit_cast(bf16x8, w);
;     }
; #pragma unroll
;     for (int k = 0; k < 4; ++k) {
;         o[0] = __builtin_amdgcn_mfma_f32_32x32x16_bf16(pa[k], vf[0][k], o[0], 0, 0, 0);
;         o[1] = __builtin_amdgcn_mfma_f32_32x32x16_bf16(pa[k], vf[1][k], o[1], 0, 0, 0);
;     }
; template <bool DIFF>
; __device__ __forceinline__ void attn_item(const Params& p, int l, int I, LAS unsigned char* lds, const int tid) {
;     ...
;         if (DIFF) {
; #pragma unroll
;             for (int r = 0; r < 16; ++r) negm2[r] = -mref2;
;             f32x16 s0 = negm2, s1 = negm2;
;             bf16x8 kg[2][2];
; #pragma unroll
;             for (int d0 = 0; d0 < 2; ++d0) { kg[d0][0] = *(const LAS bf16x8*)(kb + 4096 + d0 * 2048); kg[d0][1] = *(const LAS bf16x8*)(kb + 4096 + d0 * 2048 + 512); }
; #pragma unroll
;             for (int d0 = 0; d0 < 2; ++d0) {
;                 s0 = __builtin_amdgcn_mfma_f32_32x32x16_bf16(kg[d0][0], qf[2 + d0], s0, 0, 0, 0);
;                 s1 = __builtin_amdgcn_mfma_f32_32x32x16_bf16(kg[d0][1], qf[2 + d0], s1, 0, 0, 0);
;             }
;             softmax_pv(s0, s1, mref2, negm2, l2, o2, scr + 32, vf, t == 0, r32, hi);
.Ldr_cont_01:
	v_exp_f32_e32 v80, v80
	v_exp_f32_e32 v81, v81
	v_exp_f32_e32 v82, v82
	v_exp_f32_e32 v83, v83
	v_exp_f32_e32 v84, v84
	v_exp_f32_e32 v85, v85
	v_exp_f32_e32 v86, v86
	v_exp_f32_e32 v87, v87
	v_cvt_pk_bf16_f32 v210, v80, v81
	v_cvt_pk_bf16_f32 v211, v82, v83
	v_cvt_pk_bf16_f32 v212, v84, v85
	v_cvt_pk_bf16_f32 v213, v86, v87
	v_add_f32_e32 v214, v80, v82
	v_add_f32_e32 v215, v81, v83
	v_add_f32_e32 v214, v214, v84
	v_add_f32_e32 v215, v215, v85
	v_add_f32_e32 v214, v214, v86
	v_add_f32_e32 v215, v215, v87
	v_mfma_f32_32x32x16_bf16 v[0:15], v[210:213], v[128:131], v[0:15]
	v_mfma_f32_32x32x16_bf16 v[16:31], v[210:213], v[144:147], v[16:31]
	v_exp_f32_e32 v88, v88
	v_exp_f32_e32 v89, v89
	v_exp_f32_e32 v90, v90
	v_exp_f32_e32 v91, v91
	v_exp_f32_e32 v92, v92
	v_exp_f32_e32 v93, v93
	v_exp_f32_e32 v94, v94
	v_exp_f32_e32 v95, v95
	v_cvt_pk_bf16_f32 v248, v88, v89
	v_cvt_pk_bf16_f32 v249, v90, v91
	v_cvt_pk_bf16_f32 v250, v92, v93
	v_cvt_pk_bf16_f32 v251, v94, v95
	v_add_f32_e32 v214, v214, v88
	v_add_f32_e32 v215, v215, v89
	v_add_f32_e32 v214, v214, v90
	v_add_f32_e32 v215, v215, v91
	v_add_f32_e32 v214, v214, v92
	v_add_f32_e32 v215, v215, v93
	v_add_f32_e32 v214, v214, v94
	v_add_f32_e32 v215, v215, v95
	v_mfma_f32_32x32x16_bf16 v[0:15], v[248:251], v[132:135], v[0:15]
	v_mfma_f32_32x32x16_bf16 v[16:31], v[248:251], v[148:151], v[16:31]
	s_waitcnt lgkmcnt(0)
	v_mfma_f32_32x32x16_bf16 v[80:95], v[234:237], v[104:107], v[194:209]
	v_mfma_f32_32x32x16_bf16 v[80:95], v[242:245], v[112:115], v[80:95]
	v_exp_f32_e32 v64, v64
	v_exp_f32_e32 v65, v65
	v_exp_f32_e32 v66, v66
	v_exp_f32_e32 v67, v67
	v_exp_f32_e32 v68, v68
	v_exp_f32_e32 v69, v69
	v_exp_f32_e32 v70, v70
	v_exp_f32_e32 v71, v71
	v_cvt_pk_bf16_f32 v210, v64, v65
	v_cvt_pk_bf16_f32 v211, v66, v67
	v_cvt_pk_bf16_f32 v212, v68, v69
	v_cvt_pk_bf16_f32 v213, v70, v71
	v_add_f32_e32 v214, v214, v64
	v_add_f32_e32 v215, v215, v65
	v_add_f32_e32 v214, v214, v66
	v_add_f32_e32 v215, v215, v67
	v_add_f32_e32 v214, v214, v68
	v_add_f32_e32 v215, v215, v69
	v_add_f32_e32 v214, v214, v70
	v_add_f32_e32 v215, v215, v71
	v_mfma_f32_32x32x16_bf16 v[0:15], v[210:213], v[136:139], v[0:15]
	v_mfma_f32_32x32x16_bf16 v[16:31], v[210:213], v[152:155], v[16:31]
	v_exp_f32_e32 v72, v72
	v_exp_f32_e32 v73, v73
	v_exp_f32_e32 v74, v74
	v_exp_f32_e32 v75, v75
	v_exp_f32_e32 v76, v76
	v_exp_f32_e32 v77, v77
	v_exp_f32_e32 v78, v78
	v_exp_f32_e32 v79, v79
	v_cvt_pk_bf16_f32 v248, v72, v73
	v_cvt_pk_bf16_f32 v249, v74, v75
	v_cvt_pk_bf16_f32 v250, v76, v77
	v_cvt_pk_bf16_f32 v251, v78, v79
	v_add_f32_e32 v214, v214, v72
	v_add_f32_e32 v215, v215, v73
	v_add_f32_e32 v214, v214, v74
	v_add_f32_e32 v215, v215, v75
	v_add_f32_e32 v214, v214, v76
	v_add_f32_e32 v215, v215, v77
	v_add_f32_e32 v214, v214, v78
	v_add_f32_e32 v215, v215, v79
	v_mfma_f32_32x32x16_bf16 v[64:79], v[238:241], v[104:107], v[194:209]
	v_mfma_f32_32x32x16_bf16 v[64:79], v[188:191], v[112:115], v[64:79]
	v_mfma_f32_32x32x16_bf16 v[0:15], v[248:251], v[140:143], v[0:15]
	v_mfma_f32_32x32x16_bf16 v[16:31], v[248:251], v[156:159], v[16:31]
	v_add_f32_e32 v214, v214, v215
	v_add_f32_e32 v161, v161, v214
	v_cmp_lt_f32_e32 vcc, 0x47800000, v214
	s_cbranch_vccnz .Ldp_01
.Ldpc_01:
	ds_read_b128 v[234:237], v187 offset:24576
	ds_read_b128 v[238:241], v187 offset:25088
	ds_read_b128 v[242:245], v187 offset:26624
	ds_read_b128 v[188:191], v187 offset:27136
	ds_read_b64_tr_b16 v[128:129], v163 offset:32768
	ds_read_b64_tr_b16 v[130:131], v163 offset:33280
	ds_read_b64_tr_b16 v[144:145], v163 offset:36864
	ds_read_b64_tr_b16 v[146:147], v163 offset:37376
	ds_read_b64_tr_b16 v[132:133], v163 offset:33792
	ds_read_b64_tr_b16 v[134:135], v163 offset:34304
	ds_read_b64_tr_b16 v[148:149], v163 offset:37888
	ds_read_b64_tr_b16 v[150:151], v163 offset:38400
	s_waitcnt lgkmcnt(7)
	ds_read_b64_tr_b16 v[136:137], v163 offset:34816
	ds_read_b64_tr_b16 v[138:139], v163 offset:35328
	ds_read_b64_tr_b16 v[152:153], v163 offset:38912
	ds_read_b64_tr_b16 v[154:155], v163 offset:39424
	ds_read_b64_tr_b16 v[140:141], v163 offset:35840
	ds_read_b64_tr_b16 v[142:143], v163 offset:36352
	ds_read_b64_tr_b16 v[156:157], v163 offset:39936
	ds_read_b64_tr_b16 v[158:159], v163 offset:40448
; #define LAS __attribute__((address_space(3)))
; __device__ __forceinline__ unsigned cvt_pk_bf16(float lo, float hi) { const f32x2 v = {lo, hi}; const bf16x2_t b = __builtin_convertvector(v, bf16x2_t); return __builtin_bit_cast(unsigned, b); }
; __device__ __forceinline__ void softmax_pv(f32x16& s0, f32x16& s1, float& mref, f32x16& negm, float& lsum, f32x16 (&o)[2], LAS float* fac, const bf16x8 (&vf)[2][4], bool first, int r32, int hi) {
;     ...
;     float ps0 = 0.f, ps1 = 0.f;
; #pragma unroll
;     for (int r = 0; r < 16; ++r) { s0[r] = __builtin_amdgcn_exp2f(s0[r]); s1[r] = __builtin_amdgcn_exp2f(s1[r]); ps0 += s0[r]; ps1 += s1[r]; }
;     lsum += ps0 + ps1;
;     bf16x8 pa[4];
; #pragma unroll
;     for (int k = 0; k < 4; ++k) {
;         const f32x16& s = (k < 2) ? s0 : s1; const int rb = 8 * (k & 1);
;         u32x4 w; w.x = cvt_pk_bf16(s[rb + 0], s[rb + 1]); w.y = cvt_pk_bf16(s[rb + 2], s[rb + 3]); w.z = cvt_pk_bf16(s[rb + 4], s[rb + 5]); w.w = cvt_pk_bf16(s[rb + 6], s[rb + 7]);
;         pa[k] = __builtin_bit_cast(bf16x8, w);
;     }
; #pragma unroll
;     for (int k = 0; k < 4; ++k) {
;         o[0] = __builtin_amdgcn_mfma_f32_32x32x16_bf16(pa[k], vf[0][k], o[0], 0, 0, 0);
;         o[1] = __builtin_amdgcn_mfma_f32_32x32x16_bf16(pa[k], vf[1][k], o[1], 0, 0, 0);
;     }
; template <bool DIFF>
; __device__ __forceinline__ void attn_item(const Params& p, int l, int I, LAS unsigned char* lds, const int tid) {
;     ...
;         if (DIFF) {
; #pragma unroll
;             for (int r = 0; r < 16; ++r) negm2[r] = -mref2;
;             f32x16 s0 = negm2, s1 = negm2;
;             bf16x8 kg[2][2];
; #pragma unroll
;             for (int d0 = 0; d0 < 2; ++d0) { kg[d0][0] = *(const LAS bf16x8*)(kb + 4096 + d0 * 2048); kg[d0][1] = *(const LAS bf16x8*)(kb + 4096 + d0 * 2048 + 512); }
; #pragma unroll
;             for (int d0 = 0; d0 < 2; ++d0) {
;                 s0 = __builtin_amdgcn_mfma_f32_32x32x16_bf16(kg[d0][0], qf[2 + d0], s0, 0, 0, 0);
;                 s1 = __builtin_amdgcn_mfma_f32_32x32x16_bf16(kg[d0][1], qf[2 + d0], s1, 0, 0, 0);
;             }
;             softmax_pv(s0, s1, mref2, negm2, l2, o2, scr + 32, vf, t == 0, r32, hi);
.Ldr_cont_10:
	v_exp_f32_e32 v80, v80
	v_exp_f32_e32 v81, v81
	v_exp_f32_e32 v82, v82
	v_exp_f32_e32 v83, v83
	v_exp_f32_e32 v84, v84
	v_exp_f32_e32 v85, v85
	v_exp_f32_e32 v86, v86
	v_exp_f32_e32 v87, v87
	v_cvt_pk_bf16_f32 v210, v80, v81
	v_cvt_pk_bf16_f32 v211, v82, v83
	v_cvt_pk_bf16_f32 v212, v84, v85
	v_cvt_pk_bf16_f32 v213, v86, v87
	v_add_f32_e32 v214, v80, v82
	v_add_f32_e32 v215, v81, v83
	v_add_f32_e32 v214, v214, v84
	v_add_f32_e32 v215, v215, v85
	v_add_f32_e32 v214, v214, v86
	v_add_f32_e32 v215, v215, v87
	s_waitcnt lgkmcnt(12)
	v_mfma_f32_32x32x16_bf16 v[32:47], v[210:213], v[128:131], v[32:47]
	v_mfma_f32_32x32x16_bf16 v[48:63], v[210:213], v[144:147], v[48:63]
	v_exp_f32_e32 v88, v88
	v_exp_f32_e32 v89, v89
	v_exp_f32_e32 v90, v90
	v_exp_f32_e32 v91, v91
	v_exp_f32_e32 v92, v92
	v_exp_f32_e32 v93, v93
	v_exp_f32_e32 v94, v94
	v_exp_f32_e32 v95, v95
	v_cvt_pk_bf16_f32 v248, v88, v89
	v_cvt_pk_bf16_f32 v249, v90, v91
	v_cvt_pk_bf16_f32 v250, v92, v93
	v_cvt_pk_bf16_f32 v251, v94, v95
	v_add_f32_e32 v214, v214, v88
	v_add_f32_e32 v215, v215, v89
	v_add_f32_e32 v214, v214, v90
	v_add_f32_e32 v215, v215, v91
	v_add_f32_e32 v214, v214, v92
	v_add_f32_e32 v215, v215, v93
	v_add_f32_e32 v214, v214, v94
	v_add_f32_e32 v215, v215, v95
	s_waitcnt lgkmcnt(8)
	v_mfma_f32_32x32x16_bf16 v[32:47], v[248:251], v[132:135], v[32:47]
	v_mfma_f32_32x32x16_bf16 v[48:63], v[248:251], v[148:151], v[48:63]
	v_mfma_f32_32x32x16_bf16 v[80:95], v[234:237], v[120:123], v[218:233]
	v_mfma_f32_32x32x16_bf16 v[80:95], v[242:245], v[124:127], v[80:95]
	v_exp_f32_e32 v64, v64
	v_exp_f32_e32 v65, v65
	v_exp_f32_e32 v66, v66
	v_exp_f32_e32 v67, v67
	v_exp_f32_e32 v68, v68
	v_exp_f32_e32 v69, v69
	v_exp_f32_e32 v70, v70
	v_exp_f32_e32 v71, v71
	v_cvt_pk_bf16_f32 v210, v64, v65
	v_cvt_pk_bf16_f32 v211, v66, v67
	v_cvt_pk_bf16_f32 v212, v68, v69
	v_cvt_pk_bf16_f32 v213, v70, v71
	v_add_f32_e32 v214, v214, v64
	v_add_f32_e32 v215, v215, v65
	v_add_f32_e32 v214, v214, v66
	v_add_f32_e32 v215, v215, v67
	v_add_f32_e32 v214, v214, v68
	v_add_f32_e32 v215, v215, v69
	v_add_f32_e32 v214, v214, v70
	v_add_f32_e32 v215, v215, v71
	s_waitcnt lgkmcnt(4)
	v_mfma_f32_32x32x16_bf16 v[32:47], v[210:213], v[136:139], v[32:47]
	v_mfma_f32_32x32x16_bf16 v[48:63], v[210:213], v[152:155], v[48:63]
	v_exp_f32_e32 v72, v72
	v_exp_f32_e32 v73, v73
	v_exp_f32_e32 v74, v74
	v_exp_f32_e32 v75, v75
	v_exp_f32_e32 v76, v76
	v_exp_f32_e32 v77, v77
	v_exp_f32_e32 v78, v78
	v_exp_f32_e32 v79, v79
	v_cvt_pk_bf16_f32 v248, v72, v73
	v_cvt_pk_bf16_f32 v249, v74, v75
	v_cvt_pk_bf16_f32 v250, v76, v77
	v_cvt_pk_bf16_f32 v251, v78, v79
	v_add_f32_e32 v214, v214, v72
	v_add_f32_e32 v215, v215, v73
	v_add_f32_e32 v214, v214, v74
	v_add_f32_e32 v215, v215, v75
	v_add_f32_e32 v214, v214, v76
	v_add_f32_e32 v215, v215, v77
	v_add_f32_e32 v214, v214, v78
	v_add_f32_e32 v215, v215, v79
	v_mfma_f32_32x32x16_bf16 v[64:79], v[238:241], v[120:123], v[218:233]
	v_mfma_f32_32x32x16_bf16 v[64:79], v[188:191], v[124:127], v[64:79]
	s_waitcnt lgkmcnt(0)
	v_mfma_f32_32x32x16_bf16 v[32:47], v[248:251], v[140:143], v[32:47]
	v_mfma_f32_32x32x16_bf16 v[48:63], v[248:251], v[156:159], v[48:63]
	v_add_f32_e32 v214, v214, v215
	v_add_f32_e32 v162, v162, v214
	v_cmp_lt_f32_e32 vcc, 0x47800000, v214
	s_cbranch_vccnz .Ldp_10
.Ldpc_10:
	s_nop 5
.Ldr_cont_11:
	v_exp_f32_e32 v80, v80
	v_exp_f32_e32 v81, v81
	v_exp_f32_e32 v82, v82
	v_exp_f32_e32 v83, v83
	v_exp_f32_e32 v84, v84
	v_exp_f32_e32 v85, v85
	v_exp_f32_e32 v86, v86
	v_exp_f32_e32 v87, v87
	v_cvt_pk_bf16_f32 v210, v80, v81
	v_cvt_pk_bf16_f32 v211, v82, v83
	v_cvt_pk_bf16_f32 v212, v84, v85
	v_cvt_pk_bf16_f32 v213, v86, v87
	v_add_f32_e32 v214, v80, v82
	v_add_f32_e32 v215, v81, v83
	v_add_f32_e32 v214, v214, v84
	v_add_f32_e32 v215, v215, v85
	v_add_f32_e32 v214, v214, v86
	v_add_f32_e32 v215, v215, v87
	v_mfma_f32_32x32x16_bf16 v[0:15], v[210:213], v[128:131], v[0:15]
	v_mfma_f32_32x32x16_bf16 v[16:31], v[210:213], v[144:147], v[16:31]
	v_exp_f32_e32 v88, v88
	v_exp_f32_e32 v89, v89
	v_exp_f32_e32 v90, v90
	v_exp_f32_e32 v91, v91
	v_exp_f32_e32 v92, v92
	v_exp_f32_e32 v93, v93
	v_exp_f32_e32 v94, v94
	v_exp_f32_e32 v95, v95
	v_cvt_pk_bf16_f32 v248, v88, v89
	v_cvt_pk_bf16_f32 v249, v90, v91
	v_cvt_pk_bf16_f32 v250, v92, v93
	v_cvt_pk_bf16_f32 v251, v94, v95
	v_add_f32_e32 v214, v214, v88
	v_add_f32_e32 v215, v215, v89
	v_add_f32_e32 v214, v214, v90
	v_add_f32_e32 v215, v215, v91
	v_add_f32_e32 v214, v214, v92
	v_add_f32_e32 v215, v215, v93
	v_add_f32_e32 v214, v214, v94
	v_add_f32_e32 v215, v215, v95
	v_mfma_f32_32x32x16_bf16 v[0:15], v[248:251], v[132:135], v[0:15]
	v_mfma_f32_32x32x16_bf16 v[16:31], v[248:251], v[148:151], v[16:31]
	v_exp_f32_e32 v64, v64
	v_exp_f32_e32 v65, v65
	v_exp_f32_e32 v66, v66
	v_exp_f32_e32 v67, v67
	v_exp_f32_e32 v68, v68
	v_exp_f32_e32 v69, v69
	v_exp_f32_e32 v70, v70
	v_exp_f32_e32 v71, v71
	v_cvt_pk_bf16_f32 v210, v64, v65
	v_cvt_pk_bf16_f32 v211, v66, v67
	v_cvt_pk_bf16_f32 v212, v68, v69
	v_cvt_pk_bf16_f32 v213, v70, v71
	v_add_f32_e32 v214, v214, v64
	v_add_f32_e32 v215, v215, v65
	v_add_f32_e32 v214, v214, v66
	v_add_f32_e32 v215, v215, v67
	v_add_f32_e32 v214, v214, v68
	v_add_f32_e32 v215, v215, v69
	v_add_f32_e32 v214, v214, v70
	v_add_f32_e32 v215, v215, v71
	v_mfma_f32_32x32x16_bf16 v[0:15], v[210:213], v[136:139], v[0:15]
	v_mfma_f32_32x32x16_bf16 v[16:31], v[210:213], v[152:155], v[16:31]
	v_exp_f32_e32 v72, v72
	v_exp_f32_e32 v73, v73
	v_exp_f32_e32 v74, v74
	v_exp_f32_e32 v75, v75
	v_exp_f32_e32 v76, v76
	v_exp_f32_e32 v77, v77
	v_exp_f32_e32 v78, v78
	v_exp_f32_e32 v79, v79
	v_cvt_pk_bf16_f32 v248, v72, v73
	v_cvt_pk_bf16_f32 v249, v74, v75
	v_cvt_pk_bf16_f32 v250, v76, v77
	v_cvt_pk_bf16_f32 v251, v78, v79
	v_add_f32_e32 v214, v214, v72
	v_add_f32_e32 v215, v215, v73
	v_add_f32_e32 v214, v214, v74
	v_add_f32_e32 v215, v215, v75
	v_add_f32_e32 v214, v214, v76
	v_add_f32_e32 v215, v215, v77
	v_add_f32_e32 v214, v214, v78
	v_add_f32_e32 v215, v215, v79
	v_mfma_f32_32x32x16_bf16 v[0:15], v[248:251], v[140:143], v[0:15]
	v_mfma_f32_32x32x16_bf16 v[16:31], v[248:251], v[156:159], v[16:31]
	v_add_f32_e32 v214, v214, v215
	v_add_f32_e32 v161, v161, v214
	v_cmp_lt_f32_e32 vcc, 0x47800000, v214
	s_cbranch_vccnz .Ldp_11
; #define LAS __attribute__((address_space(3)))
; __device__ __forceinline__ int crow(int r, int hi) { return (r & 3) + 8 * (r >> 2) + 4 * hi; }
; #define tid fresh_tid(wid1)
; __device__ __forceinline__ void softmax_pv(f32x16& s0, f32x16& s1, float& mref, f32x16& negm, float& lsum, f32x16 (&o)[2], LAS float* fac, const bf16x8 (&vf)[2][4], bool first, int r32, int hi) {
;     ...
;     if (__builtin_expect(first || __any(mx > 16.0f), 0)) {
;         const float d = first ? mx : fmaxf(mx, 0.f);
;         const float f = __builtin_amdgcn_exp2f(-d);
;         lsum *= f; mref += d;
; #pragma unroll
;         for (int r = 0; r < 16; ++r) { s0[r] -= d; s1[r] -= d; negm[r] = -mref; }
;         if (hi == 0) fac[r32] = f;
;         asm volatile("s_waitcnt lgkmcnt(0)" ::: "memory");
; #pragma unroll
;         for (int r = 0; r < 16; ++r) { const float ff = fac[crow(r, hi)]; o[0][r] *= ff; o[1][r] *= ff; }
;     }
; template <bool DIFF>
; __device__ __forceinline__ void attn_item(const Params& p, int l, int I, LAS unsigned char* lds, const int tid) {
;     ...
;     auto lwrite = [&](int slot, const int j) {
;         LAS unsigned char* sb = lds + slot * AT_SLOT + j * AT_SUB;
;         *(LAS u32x4*)(sb + kw0) = g0[j]; *(LAS u32x4*)(sb + vw) = g1[j];
;         if (!DIFF) { if (tid < 256) *(LAS u32x4*)(sb + kw2) = g2[j]; }
;     };
.Ldpc_11:
	s_andn2_b64 vcc, exec, s[8:9]
	s_cbranch_vccnz .LBB0_492
	s_andn2_b32 s8, 1, s34
	s_mul_i32 s8, s8, 0xa000
	s_add_i32 s8, s8, 0
	v_add_u32_e32 v128, s8, v174
	v_add_u32_e32 v129, s8, v179
	s_waitcnt vmcnt(3)
	ds_write_b128 v128, v[96:99]
	s_waitcnt vmcnt(2)
	ds_write_b128 v129, v[100:103] offset:12288
	s_waitcnt vmcnt(1)
	ds_write_b128 v128, v[108:111] offset:20480
	s_waitcnt vmcnt(0)
	ds_write_b128 v129, v[116:119] offset:32768
	s_branch .LBB0_492
.Ldr_first_00:
	v_max3_f32 v210, v80, v81, v82
	v_max3_f32 v211, v64, v65, v66
	v_max3_f32 v210, v210, v83, v84
	v_max3_f32 v211, v211, v67, v68
	v_max3_f32 v210, v210, v85, v86
	v_max3_f32 v211, v211, v69, v70
	v_max3_f32 v210, v210, v87, v88
	v_max3_f32 v211, v211, v71, v72
	v_max3_f32 v210, v210, v89, v90
	v_max3_f32 v211, v211, v73, v74
	v_max3_f32 v210, v210, v91, v92
	v_max3_f32 v211, v211, v75, v76
	v_max3_f32 v210, v210, v93, v94
	v_max3_f32 v211, v211, v77, v78
	v_max_f32_e32 v212, v95, v79
	v_max3_f32 v210, v210, v211, v212
	v_mov_b32_e32 v211, v210
	s_nop 1
	v_permlane32_swap_b32_e32 v210, v211
	v_max_f32_e32 v160, v210, v211
	v_exp_f32_e64 v246, -v160
	v_sub_f32_e32 v80, v80, v160
	v_sub_f32_e32 v64, v64, v160
	v_sub_f32_e32 v81, v81, v160
	v_sub_f32_e32 v65, v65, v160
	v_sub_f32_e32 v82, v82, v160
	v_sub_f32_e32 v66, v66, v160
	v_sub_f32_e32 v83, v83, v160
	v_sub_f32_e32 v67, v67, v160
	v_sub_f32_e32 v84, v84, v160
	v_sub_f32_e32 v68, v68, v160
	v_sub_f32_e32 v85, v85, v160
	v_sub_f32_e32 v69, v69, v160
	v_sub_f32_e32 v86, v86, v160
	v_sub_f32_e32 v70, v70, v160
	v_sub_f32_e32 v87, v87, v160
	v_sub_f32_e32 v71, v71, v160
	v_sub_f32_e32 v88, v88, v160
	v_sub_f32_e32 v72, v72, v160
	v_sub_f32_e32 v89, v89, v160
	v_sub_f32_e32 v73, v73, v160
	v_sub_f32_e32 v90, v90, v160
	v_sub_f32_e32 v74, v74, v160
	v_sub_f32_e32 v91, v91, v160
	v_sub_f32_e32 v75, v75, v160
	v_sub_f32_e32 v92, v92, v160
	v_sub_f32_e32 v76, v76, v160
	v_sub_f32_e32 v93, v93, v160
	v_sub_f32_e32 v77, v77, v160
	v_sub_f32_e32 v94, v94, v160
	v_sub_f32_e32 v78, v78, v160
	v_sub_f32_e32 v95, v95, v160
	v_sub_f32_e32 v79, v79, v160
	s_and_saveexec_b64 s[20:21], s[4:5]
	ds_write_b32 v180, v246
	s_or_b64 exec, exec, s[20:21]
	v_add_f32_e32 v186, v186, v160
	v_mul_f32_e32 v162, v162, v246
	v_xor_b32_e32 v194, 0x80000000, v186
	v_mov_b32_e32 v195, v194
	v_mov_b32_e32 v196, v194
	v_mov_b32_e32 v197, v194
	v_mov_b32_e32 v198, v194
	v_mov_b32_e32 v199, v194
	v_mov_b32_e32 v200, v194
	v_mov_b32_e32 v201, v194
	v_mov_b32_e32 v202, v194
	v_mov_b32_e32 v203, v194
	v_mov_b32_e32 v204, v194
	v_mov_b32_e32 v205, v194
	v_mov_b32_e32 v206, v194
	v_mov_b32_e32 v207, v194
	v_mov_b32_e32 v208, v194
	v_mov_b32_e32 v209, v194
	s_waitcnt lgkmcnt(0)
	v_add_u32_e32 v160, s35, v192
	ds_read_b128 v[210:213], v160
	ds_read_b128 v[248:251], v160 offset:32
	s_waitcnt lgkmcnt(0)
	v_pk_mul_f32 v[32:33], v[32:33], v[210:211]
	v_pk_mul_f32 v[34:35], v[34:35], v[212:213]
	v_pk_mul_f32 v[36:37], v[36:37], v[248:249]
	v_pk_mul_f32 v[38:39], v[38:39], v[250:251]
	v_pk_mul_f32 v[48:49], v[48:49], v[210:211]
	v_pk_mul_f32 v[50:51], v[50:51], v[212:213]
	v_pk_mul_f32 v[52:53], v[52:53], v[248:249]
	v_pk_mul_f32 v[54:55], v[54:55], v[250:251]
	ds_read_b128 v[210:213], v160 offset:64
	ds_read_b128 v[248:251], v160 offset:96
	s_waitcnt lgkmcnt(0)
	v_pk_mul_f32 v[40:41], v[40:41], v[210:211]
	v_pk_mul_f32 v[42:43], v[42:43], v[212:213]
	v_pk_mul_f32 v[44:45], v[44:45], v[248:249]
	v_pk_mul_f32 v[46:47], v[46:47], v[250:251]
	v_pk_mul_f32 v[56:57], v[56:57], v[210:211]
	v_pk_mul_f32 v[58:59], v[58:59], v[212:213]
	v_pk_mul_f32 v[60:61], v[60:61], v[248:249]
	v_pk_mul_f32 v[62:63], v[62:63], v[250:251]
	s_branch .Ldr_cont_00
.Ldp_00:
	v_mov_b32_e32 v210, v214
	v_mov_b32_e32 v211, v214
	s_nop 1
	v_permlane32_swap_b32_e32 v210, v211
	v_add_f32_e32 v210, v210, v211
	v_log_f32_e32 v160, v210
	s_nop 0
	v_ceil_f32_e32 v160, v160
	v_max_f32_e32 v160, 0, v160
	v_exp_f32_e64 v246, -v160
	s_nop 7
	s_and_saveexec_b64 s[20:21], s[4:5]
	ds_write_b32 v180, v246
	s_or_b64 exec, exec, s[20:21]
	v_add_f32_e32 v186, v186, v160
	v_mul_f32_e32 v162, v162, v246
	v_xor_b32_e32 v194, 0x80000000, v186
	v_mov_b32_e32 v195, v194
	v_mov_b32_e32 v196, v194
	v_mov_b32_e32 v197, v194
	v_mov_b32_e32 v198, v194
	v_mov_b32_e32 v199, v194
	v_mov_b32_e32 v200, v194
	v_mov_b32_e32 v201, v194
	v_mov_b32_e32 v202, v194
	v_mov_b32_e32 v203, v194
	v_mov_b32_e32 v204, v194
	v_mov_b32_e32 v205, v194
	v_mov_b32_e32 v206, v194
	v_mov_b32_e32 v207, v194
	v_mov_b32_e32 v208, v194
	v_mov_b32_e32 v209, v194
	s_waitcnt lgkmcnt(0)
	v_add_u32_e32 v160, s35, v192
	ds_read_b128 v[210:213], v160
	ds_read_b128 v[248:251], v160 offset:32
	s_waitcnt lgkmcnt(0)
	v_pk_mul_f32 v[32:33], v[32:33], v[210:211]
	v_pk_mul_f32 v[34:35], v[34:35], v[212:213]
	v_pk_mul_f32 v[36:37], v[36:37], v[248:249]
	v_pk_mul_f32 v[38:39], v[38:39], v[250:251]
	v_pk_mul_f32 v[48:49], v[48:49], v[210:211]
	v_pk_mul_f32 v[50:51], v[50:51], v[212:213]
	v_pk_mul_f32 v[52:53], v[52:53], v[248:249]
	v_pk_mul_f32 v[54:55], v[54:55], v[250:251]
	ds_read_b128 v[210:213], v160 offset:64
	ds_read_b128 v[248:251], v160 offset:96
	s_waitcnt lgkmcnt(0)
	v_pk_mul_f32 v[40:41], v[40:41], v[210:211]
	v_pk_mul_f32 v[42:43], v[42:43], v[212:213]
	v_pk_mul_f32 v[44:45], v[44:45], v[248:249]
	v_pk_mul_f32 v[46:47], v[46:47], v[250:251]
	v_pk_mul_f32 v[56:57], v[56:57], v[210:211]
	v_pk_mul_f32 v[58:59], v[58:59], v[212:213]
	v_pk_mul_f32 v[60:61], v[60:61], v[248:249]
	v_pk_mul_f32 v[62:63], v[62:63], v[250:251]
	s_branch .Ldpc_00
; __device__ __forceinline__ int crow(int r, int hi) { return (r & 3) + 8 * (r >> 2) + 4 * hi; }
; __device__ __forceinline__ float half_max(float m) { auto rr = __builtin_amdgcn_permlane32_swap(__float_as_uint(m), __float_as_uint(m), false, false); return fmaxf(__uint_as_float(rr[0]), __uint_as_float(rr[1])); }
; __device__ __forceinline__ void softmax_pv(f32x16& s0, f32x16& s1, float& mref, f32x16& negm, float& lsum, f32x16 (&o)[2], LAS float* fac, const bf16x8 (&vf)[2][4], bool first, int r32, int hi) {
;     float ma = fmaxf(fmaxf(s0[0], s0[1]), s0[2]), mb = fmaxf(fmaxf(s1[0], s1[1]), s1[2]);
; #pragma unroll
;     for (int r = 3; r < 15; r += 2) { ma = fmaxf(fmaxf(ma, s0[r]), s0[r + 1]); mb = fmaxf(fmaxf(mb, s1[r]), s1[r + 1]); }
;     float mx = fmaxf(fmaxf(ma, mb), fmaxf(s0[15], s1[15]));
;     mx = half_max(mx);
;     if (__builtin_expect(first || __any(mx > 16.0f), 0)) {
;         const float d = first ? mx : fmaxf(mx, 0.f);
;         const float f = __builtin_amdgcn_exp2f(-d);
;         lsum *= f; mref += d;
; #pragma unroll
;         for (int r = 0; r < 16; ++r) { s0[r] -= d; s1[r] -= d; negm[r] = -mref; }
;         if (hi == 0) fac[r32] = f;
;         asm volatile("s_waitcnt lgkmcnt(0)" ::: "memory");
; #pragma unroll
;         for (int r = 0; r < 16; ++r) { const float ff = fac[crow(r, hi)]; o[0][r] *= ff; o[1][r] *= ff; }
;     }
.Ldr_first_01:
	v_max3_f32 v210, v80, v81, v82
	v_max3_f32 v211, v64, v65, v66
	v_max3_f32 v210, v210, v83, v84
	v_max3_f32 v211, v211, v67, v68
	v_max3_f32 v210, v210, v85, v86
	v_max3_f32 v211, v211, v69, v70
	v_max3_f32 v210, v210, v87, v88
	v_max3_f32 v211, v211, v71, v72
	v_max3_f32 v210, v210, v89, v90
	v_max3_f32 v211, v211, v73, v74
	v_max3_f32 v210, v210, v91, v92
	v_max3_f32 v211, v211, v75, v76
	v_max3_f32 v210, v210, v93, v94
	v_max3_f32 v211, v211, v77, v78
	v_max_f32_e32 v212, v95, v79
	v_max3_f32 v210, v210, v211, v212
	v_mov_b32_e32 v211, v210
	s_nop 1
	v_permlane32_swap_b32_e32 v210, v211
	v_max_f32_e32 v160, v210, v211
	v_exp_f32_e64 v246, -v160
	v_sub_f32_e32 v80, v80, v160
	v_sub_f32_e32 v64, v64, v160
	v_sub_f32_e32 v81, v81, v160
	v_sub_f32_e32 v65, v65, v160
	v_sub_f32_e32 v82, v82, v160
	v_sub_f32_e32 v66, v66, v160
	v_sub_f32_e32 v83, v83, v160
	v_sub_f32_e32 v67, v67, v160
	v_sub_f32_e32 v84, v84, v160
	v_sub_f32_e32 v68, v68, v160
	v_sub_f32_e32 v85, v85, v160
	v_sub_f32_e32 v69, v69, v160
	v_sub_f32_e32 v86, v86, v160
	v_sub_f32_e32 v70, v70, v160
	v_sub_f32_e32 v87, v87, v160
	v_sub_f32_e32 v71, v71, v160
	v_sub_f32_e32 v88, v88, v160
	v_sub_f32_e32 v72, v72, v160
	v_sub_f32_e32 v89, v89, v160
	v_sub_f32_e32 v73, v73, v160
	v_sub_f32_e32 v90, v90, v160
	v_sub_f32_e32 v74, v74, v160
	v_sub_f32_e32 v91, v91, v160
	v_sub_f32_e32 v75, v75, v160
	v_sub_f32_e32 v92, v92, v160
	v_sub_f32_e32 v76, v76, v160
	v_sub_f32_e32 v93, v93, v160
	v_sub_f32_e32 v77, v77, v160
	v_sub_f32_e32 v94, v94, v160
	v_sub_f32_e32 v78, v78, v160
	v_sub_f32_e32 v95, v95, v160
	v_sub_f32_e32 v79, v79, v160
	s_and_saveexec_b64 s[20:21], s[4:5]
	ds_write_b32 v180, v246 offset:128
	s_or_b64 exec, exec, s[20:21]
	v_add_f32_e32 v185, v185, v160
	v_mul_f32_e32 v161, v161, v246
	v_xor_b32_e32 v218, 0x80000000, v185
	v_mov_b32_e32 v219, v218
	v_mov_b32_e32 v220, v218
	v_mov_b32_e32 v221, v218
	v_mov_b32_e32 v222, v218
	v_mov_b32_e32 v223, v218
	v_mov_b32_e32 v224, v218
	v_mov_b32_e32 v225, v218
	v_mov_b32_e32 v226, v218
	v_mov_b32_e32 v227, v218
	v_mov_b32_e32 v228, v218
	v_mov_b32_e32 v229, v218
	v_mov_b32_e32 v230, v218
	v_mov_b32_e32 v231, v218
	v_mov_b32_e32 v232, v218
	v_mov_b32_e32 v233, v218
	s_waitcnt lgkmcnt(0)
	v_add_u32_e32 v160, s35, v192
	ds_read_b128 v[210:213], v160 offset:128
	ds_read_b128 v[248:251], v160 offset:160
	s_waitcnt lgkmcnt(0)
	v_pk_mul_f32 v[0:1], v[0:1], v[210:211]
	v_pk_mul_f32 v[2:3], v[2:3], v[212:213]
	v_pk_mul_f32 v[4:5], v[4:5], v[248:249]
	v_pk_mul_f32 v[6:7], v[6:7], v[250:251]
	v_pk_mul_f32 v[16:17], v[16:17], v[210:211]
	v_pk_mul_f32 v[18:19], v[18:19], v[212:213]
	v_pk_mul_f32 v[20:21], v[20:21], v[248:249]
	v_pk_mul_f32 v[22:23], v[22:23], v[250:251]
	ds_read_b128 v[210:213], v160 offset:192
	ds_read_b128 v[248:251], v160 offset:224
	s_waitcnt lgkmcnt(0)
	v_pk_mul_f32 v[8:9], v[8:9], v[210:211]
	v_pk_mul_f32 v[10:11], v[10:11], v[212:213]
	v_pk_mul_f32 v[12:13], v[12:13], v[248:249]
	v_pk_mul_f32 v[14:15], v[14:15], v[250:251]
	v_pk_mul_f32 v[24:25], v[24:25], v[210:211]
	v_pk_mul_f32 v[26:27], v[26:27], v[212:213]
	v_pk_mul_f32 v[28:29], v[28:29], v[248:249]
	v_pk_mul_f32 v[30:31], v[30:31], v[250:251]
	s_branch .Ldr_cont_01
.Ldp_01:
	v_mov_b32_e32 v210, v214
	v_mov_b32_e32 v211, v214
	s_nop 1
	v_permlane32_swap_b32_e32 v210, v211
	v_add_f32_e32 v210, v210, v211
	v_log_f32_e32 v160, v210
	s_nop 0
	v_ceil_f32_e32 v160, v160
	v_max_f32_e32 v160, 0, v160
	v_exp_f32_e64 v246, -v160
	s_nop 7
	s_and_saveexec_b64 s[20:21], s[4:5]
	ds_write_b32 v180, v246 offset:128
	s_or_b64 exec, exec, s[20:21]
	v_add_f32_e32 v185, v185, v160
	v_mul_f32_e32 v161, v161, v246
	v_xor_b32_e32 v218, 0x80000000, v185
	v_mov_b32_e32 v219, v218
	v_mov_b32_e32 v220, v218
	v_mov_b32_e32 v221, v218
	v_mov_b32_e32 v222, v218
	v_mov_b32_e32 v223, v218
	v_mov_b32_e32 v224, v218
	v_mov_b32_e32 v225, v218
	v_mov_b32_e32 v226, v218
	v_mov_b32_e32 v227, v218
	v_mov_b32_e32 v228, v218
	v_mov_b32_e32 v229, v218
	v_mov_b32_e32 v230, v218
	v_mov_b32_e32 v231, v218
	v_mov_b32_e32 v232, v218
	v_mov_b32_e32 v233, v218
	s_waitcnt lgkmcnt(0)
	v_add_u32_e32 v160, s35, v192
	ds_read_b128 v[210:213], v160 offset:128
	ds_read_b128 v[248:251], v160 offset:160
	s_waitcnt lgkmcnt(0)
	v_pk_mul_f32 v[0:1], v[0:1], v[210:211]
	v_pk_mul_f32 v[2:3], v[2:3], v[212:213]
	v_pk_mul_f32 v[4:5], v[4:5], v[248:249]
	v_pk_mul_f32 v[6:7], v[6:7], v[250:251]
	v_pk_mul_f32 v[16:17], v[16:17], v[210:211]
	v_pk_mul_f32 v[18:19], v[18:19], v[212:213]
	v_pk_mul_f32 v[20:21], v[20:21], v[248:249]
	v_pk_mul_f32 v[22:23], v[22:23], v[250:251]
	ds_read_b128 v[210:213], v160 offset:192
	ds_read_b128 v[248:251], v160 offset:224
	s_waitcnt lgkmcnt(0)
	v_pk_mul_f32 v[8:9], v[8:9], v[210:211]
	v_pk_mul_f32 v[10:11], v[10:11], v[212:213]
	v_pk_mul_f32 v[12:13], v[12:13], v[248:249]
	v_pk_mul_f32 v[14:15], v[14:15], v[250:251]
	v_pk_mul_f32 v[24:25], v[24:25], v[210:211]
	v_pk_mul_f32 v[26:27], v[26:27], v[212:213]
	v_pk_mul_f32 v[28:29], v[28:29], v[248:249]
	v_pk_mul_f32 v[30:31], v[30:31], v[250:251]
	s_branch .Ldpc_01
